# GQA and diff attention loops: LDS fragment addresses folded to one v_add per address (base+chunk sums hoisted out of the loops)
# speedup vs baseline: 1.0413x; 1.0022x over previous
.LBB0_133:
	v_exp_f32_e32 v32, v32
	v_exp_f32_e32 v33, v33
	v_exp_f32_e32 v34, v34
	v_exp_f32_e32 v35, v35
	v_add_f32_e32 v96, 0, v32
	v_exp_f32_e32 v36, v36
	v_add_f32_e32 v96, v33, v96
	v_exp_f32_e32 v37, v37
	v_add_f32_e32 v96, v34, v96
	v_exp_f32_e32 v38, v38
	v_add_f32_e32 v96, v35, v96
	v_exp_f32_e32 v39, v39
	v_add_f32_e32 v96, v36, v96
	v_exp_f32_e32 v40, v40
	v_exp_f32_e32 v48, v48
	v_add_f32_e32 v96, v37, v96
	v_exp_f32_e32 v41, v41
	v_cvt_pk_bf16_f32 v32, v32, v33
	v_cvt_pk_bf16_f32 v33, v34, v35
	v_cvt_pk_bf16_f32 v34, v36, v37
	v_exp_f32_e32 v37, v16
	v_exp_f32_e32 v36, v0
	v_exp_f32_e32 v49, v49
	v_add_f32_e32 v96, v38, v96
	v_exp_f32_e32 v17, v17
	v_exp_f32_e32 v16, v1
	v_exp_f32_e32 v50, v50
	v_add_f32_e32 v96, v39, v96
	v_cvt_pk_bf16_f32 v35, v38, v39
	v_exp_f32_e32 v39, v18
	v_exp_f32_e32 v38, v2
	v_exp_f32_e32 v51, v51
	v_add_f32_e32 v96, v40, v96
	v_exp_f32_e32 v19, v19
	v_exp_f32_e32 v18, v3
	v_add_f32_e32 v97, 0, v48
	v_exp_f32_e32 v52, v52
	v_add_f32_e32 v96, v41, v96
	v_cvt_pk_bf16_f32 v100, v40, v41
	v_pk_add_f32 v[0:1], v[36:37], 0 op_sel_hi:[1,0]
	v_exp_f32_e32 v41, v20
	v_exp_f32_e32 v40, v4
	v_add_f32_e32 v97, v49, v97
	v_exp_f32_e32 v53, v53
	v_pk_add_f32 v[0:1], v[16:17], v[0:1]
	v_exp_f32_e32 v21, v21
	v_exp_f32_e32 v20, v5
	v_add_f32_e32 v97, v50, v97
	v_exp_f32_e32 v54, v54
	v_pk_add_f32 v[0:1], v[38:39], v[0:1]
	v_exp_f32_e32 v5, v22
	v_exp_f32_e32 v4, v6
	v_add_f32_e32 v97, v51, v97
	v_exp_f32_e32 v55, v55
	v_pk_add_f32 v[0:1], v[18:19], v[0:1]
	v_exp_f32_e32 v23, v23
	v_exp_f32_e32 v22, v7
	v_add_f32_e32 v97, v52, v97
	v_exp_f32_e32 v56, v56
	v_exp_f32_e32 v7, v24
	v_exp_f32_e32 v6, v8
	v_pk_add_f32 v[0:1], v[40:41], v[0:1]
	v_add_f32_e32 v97, v53, v97
	v_exp_f32_e32 v57, v57
	v_exp_f32_e32 v25, v25
	v_exp_f32_e32 v24, v9
	v_pk_add_f32 v[0:1], v[20:21], v[0:1]
	v_add_f32_e32 v97, v54, v97
	v_exp_f32_e32 v42, v42
	v_exp_f32_e32 v58, v58
	v_exp_f32_e32 v9, v26
	v_exp_f32_e32 v8, v10
	v_pk_add_f32 v[0:1], v[4:5], v[0:1]
	v_add_f32_e32 v97, v55, v97
	v_exp_f32_e32 v43, v43
	v_exp_f32_e32 v59, v59
	v_exp_f32_e32 v27, v27
	v_exp_f32_e32 v26, v11
	v_pk_add_f32 v[0:1], v[22:23], v[0:1]
	v_add_f32_e32 v97, v56, v97
	v_exp_f32_e32 v44, v44
	v_exp_f32_e32 v60, v60
	v_exp_f32_e32 v11, v28
	v_exp_f32_e32 v10, v12
	v_pk_add_f32 v[0:1], v[6:7], v[0:1]
	v_add_f32_e32 v97, v57, v97
	v_exp_f32_e32 v45, v45
	v_exp_f32_e32 v61, v61
	v_exp_f32_e32 v29, v29
	v_exp_f32_e32 v28, v13
	v_pk_add_f32 v[0:1], v[24:25], v[0:1]
	v_add_f32_e32 v96, v42, v96
	v_add_f32_e32 v97, v58, v97
	v_exp_f32_e32 v46, v46
	v_exp_f32_e32 v62, v62
	v_exp_f32_e32 v13, v30
	v_exp_f32_e32 v12, v14
	v_pk_add_f32 v[0:1], v[8:9], v[0:1]
	v_add_f32_e32 v96, v43, v96
	v_add_f32_e32 v97, v59, v97
	v_exp_f32_e32 v47, v47
	v_exp_f32_e32 v63, v63
	v_exp_f32_e32 v31, v31
	v_exp_f32_e32 v30, v15
	v_pk_add_f32 v[0:1], v[26:27], v[0:1]
	v_add_f32_e32 v96, v44, v96
	v_add_f32_e32 v97, v60, v97
	v_pk_add_f32 v[0:1], v[10:11], v[0:1]
	v_add_f32_e32 v96, v45, v96
	v_add_f32_e32 v97, v61, v97
	v_pk_add_f32 v[0:1], v[28:29], v[0:1]
	v_add_f32_e32 v96, v46, v96
	v_add_f32_e32 v97, v62, v97
	v_pk_add_f32 v[0:1], v[12:13], v[0:1]
	v_add_f32_e32 v96, v47, v96
	v_add_f32_e32 v97, v63, v97
	v_pk_add_f32 v[0:1], v[30:31], v[0:1]
	v_add_f32_e32 v96, v97, v96
	v_add_f32_e32 v0, v0, v1
	v_add_f32_e32 v222, 0, v96
	s_sub_i32 s8, 0x84, s13
	v_add_f32_e32 v227, 0, v0
	v_cvt_pk_bf16_f32 v0, v37, v17
	v_cvt_pk_bf16_f32 v1, v39, v19
	v_cvt_pk_bf16_f32 v2, v41, v21
	v_cvt_pk_bf16_f32 v3, v5, v23
	v_cvt_pk_bf16_f32 v96, v48, v49
	v_cvt_pk_bf16_f32 v97, v50, v51
	v_cvt_pk_bf16_f32 v98, v52, v53
	v_cvt_pk_bf16_f32 v99, v54, v55
	v_cvt_pk_bf16_f32 v101, v42, v43
	v_cvt_pk_bf16_f32 v102, v44, v45
	v_cvt_pk_bf16_f32 v103, v46, v47
	v_cvt_pk_bf16_f32 v104, v56, v57
	v_cvt_pk_bf16_f32 v105, v58, v59
	v_cvt_pk_bf16_f32 v106, v60, v61
	v_cvt_pk_bf16_f32 v107, v62, v63
	v_cvt_pk_bf16_f32 v108, v36, v16
	v_cvt_pk_bf16_f32 v109, v38, v18
	v_cvt_pk_bf16_f32 v110, v40, v20
	v_cvt_pk_bf16_f32 v111, v4, v22
	v_cvt_pk_bf16_f32 v112, v7, v25
	v_cvt_pk_bf16_f32 v113, v9, v27
	v_cvt_pk_bf16_f32 v114, v11, v29
	v_cvt_pk_bf16_f32 v115, v13, v31
	v_cvt_pk_bf16_f32 v116, v6, v24
	v_cvt_pk_bf16_f32 v117, v8, v26
	v_cvt_pk_bf16_f32 v118, v10, v28
	v_cvt_pk_bf16_f32 v119, v12, v30
	s_waitcnt lgkmcnt(0)
	v_mfma_f32_32x32x16_bf16 v[48:63], v[88:91], v[32:35], 0
	s_waitcnt vmcnt(0)
	s_mov_b32 s10, 0
	s_movk_i32 s45, 0x4000
	s_waitcnt vmcnt(0)
	s_barrier
	v_mfma_f32_32x32x16_bf16 v[32:47], v[92:95], v[32:35], 0
	v_mfma_f32_32x32x16_bf16 v[16:31], v[88:91], v[0:3], 0
	v_mfma_f32_32x32x16_bf16 v[0:15], v[92:95], v[0:3], 0
	v_mfma_f32_32x32x16_bf16 v[48:63], v[84:87], v[100:103], v[48:63]
	v_mfma_f32_32x32x16_bf16 v[32:47], v[80:83], v[100:103], v[32:47]
	v_mfma_f32_32x32x16_bf16 v[16:31], v[84:87], v[112:115], v[16:31]
	v_mfma_f32_32x32x16_bf16 v[0:15], v[80:83], v[112:115], v[0:15]
	v_mfma_f32_32x32x16_bf16 v[48:63], v[76:79], v[96:99], v[48:63]
	v_mfma_f32_32x32x16_bf16 v[32:47], v[72:75], v[96:99], v[32:47]
	v_mfma_f32_32x32x16_bf16 v[16:31], v[76:79], v[108:111], v[16:31]
	v_mfma_f32_32x32x16_bf16 v[0:15], v[72:75], v[108:111], v[0:15]
	v_mfma_f32_32x32x16_bf16 v[48:63], v[68:71], v[104:107], v[48:63]
	v_mfma_f32_32x32x16_bf16 v[32:47], v[64:67], v[104:107], v[32:47]
	v_mfma_f32_32x32x16_bf16 v[16:31], v[68:71], v[116:119], v[16:31]
	v_mfma_f32_32x32x16_bf16 v[0:15], v[64:67], v[116:119], v[0:15]
	v_readfirstlane_b32 s98, v213
	v_readfirstlane_b32 s99, v241
	v_lshlrev_b32_e32 v192, 1, v192
	v_lshlrev_b32_e32 v216, 1, v216
	v_lshlrev_b32_e32 v214, 1, v214
	v_lshlrev_b32_e32 v218, 1, v218
	v_add_u32_e32 v243, v242, v243
	v_add_u32_e32 v244, v242, v244
	v_add_u32_e32 v245, v242, v245
	v_add_u32_e32 v246, v242, v246
	v_add_u32_e32 v248, v247, v248
	v_add_u32_e32 v249, v247, v249
	v_add_u32_e32 v250, v247, v250
	v_add_u32_e32 v251, v247, v251
	s_branch .LBB0_135

.LBB0_135:
	s_and_b32 s46, s45, 0x4000
	v_add_u32_e32 v162, s46, v244
	v_add_u32_e32 v161, s46, v245
	v_add_u32_e32 v160, s46, v246
	v_add_u32_e32 v163, s46, v243
	ds_read_b128 v[164:167], v162
	ds_read_b128 v[168:171], v162 offset:4096
	ds_read_b128 v[172:175], v161
	ds_read_b128 v[176:179], v161 offset:4096
	ds_read_b128 v[180:183], v160
	ds_read_b128 v[184:187], v160 offset:4096
	s_add_i32 s2, s10, 2
	s_cmp_ge_u32 s2, s8
	s_cbranch_scc1 .LBB0_137
	s_add_i32 s2, s13, s10
	s_add_i32 s70, s2, 2
	s_lshl_b64 s[2:3], s[70:71], 13
	s_add_u32 s2, s17, s2
	s_addc_u32 s3, s18, s3
	s_sub_i32 s42, 0x4020, s46
	s_add_i32 s43, s42, s98
	s_mov_b32 m0, s43
	s_add_i32 s42, s42, s99
	global_load_lds_dwordx4 v192, s[2:3]
	s_mov_b32 m0, s42
	s_nop 0
	global_load_lds_dwordx4 v216, s[2:3]
	s_lshl_b64 s[2:3], s[70:71], 7
	s_add_u32 s2, s19, s2
	s_addc_u32 s3, s44, s3
	s_add_i32 m0, s43, 0x2000
	s_addk_i32 s42, 0x2000
	global_load_lds_dwordx4 v214, s[2:3]
	s_mov_b32 m0, s42
	s_nop 0
	global_load_lds_dwordx4 v218, s[2:3]

.LBB0_144:
	v_add_u32_e32 v161, s46, v248
	ds_read_b128 v[188:191], v161 offset:8192
	ds_read_b128 v[184:187], v161 offset:12288
	v_add_u32_e32 v161, s46, v249
	ds_read_b128 v[180:183], v161 offset:8192
	ds_read_b128 v[176:179], v161 offset:12288
	v_add_u32_e32 v161, s46, v250
	v_add_u32_e32 v160, s46, v251
	ds_read_b128 v[172:175], v161 offset:8192
	ds_read_b128 v[168:171], v161 offset:12288
	ds_read_b128 v[164:167], v160 offset:8192
	ds_read_b128 v[160:163], v160 offset:12288
	s_andn2_b64 vcc, exec, s[42:43]
	s_cbranch_vccnz .LBB0_134
	v_max_f32_e32 v228, v79, v79
	v_max_f32_e32 v229, v95, v95
	v_max_f32_e32 v228, v229, v228
	v_max3_f32 v229, v228, v80, v81
	v_max3_f32 v228, v228, v64, v65
	s_nop 0
	v_max3_f32 v228, v228, v66, v67
	v_max3_f32 v229, v229, v82, v83
	s_nop 0
	v_max3_f32 v228, v228, v68, v69
	v_max3_f32 v229, v229, v84, v85
	s_nop 0
	v_max3_f32 v228, v228, v70, v71
	v_max3_f32 v229, v229, v86, v87
	s_nop 0
	v_max3_f32 v228, v228, v72, v73
	v_max3_f32 v229, v229, v88, v89
	s_nop 0
	v_max3_f32 v228, v228, v74, v75
	v_max3_f32 v229, v229, v90, v91
	s_nop 0
	v_max3_f32 v228, v228, v76, v77
	v_max3_f32 v229, v229, v92, v93
	s_nop 0
	v_max3_f32 v228, v229, v228, v94
	s_nop 0
	v_max3_f32 v228, v228, v78, v228
	s_nop 0
	v_cmp_lt_f32_e32 vcc, s7, v228
	s_cbranch_vccz .LBB0_134
	v_cmp_lt_i32_e32 vcc, v225, v224
	s_mov_b64 s[28:29], -1
	s_nop 0
	v_cndmask_b32_e32 v229, v223, v225, vcc
	v_lshlrev_b32_e32 v229, 2, v229
	ds_bpermute_b32 v229, v229, v228
	v_max_f32_e32 v228, v228, v228
	s_waitcnt lgkmcnt(0)
	v_max_f32_e32 v229, v229, v229
	v_max_f32_e32 v228, v228, v229
	v_cmp_lt_f32_e32 vcc, s7, v228
	s_nop 1
	v_cndmask_b32_e32 v229, 0, v228, vcc
	v_exp_f32_e64 v228, -v229
	v_add_f32_e32 v210, v210, v229
	v_sub_f32_e32 v95, v95, v229
	v_sub_f32_e32 v94, v94, v229
	v_pk_mul_f32 v[30:31], v[30:31], v[228:229] op_sel_hi:[1,0]
	v_pk_mul_f32 v[28:29], v[28:29], v[228:229] op_sel_hi:[1,0]
	v_pk_mul_f32 v[26:27], v[26:27], v[228:229] op_sel_hi:[1,0]
	v_pk_mul_f32 v[24:25], v[24:25], v[228:229] op_sel_hi:[1,0]
	v_pk_mul_f32 v[22:23], v[22:23], v[228:229] op_sel_hi:[1,0]
	v_pk_mul_f32 v[20:21], v[20:21], v[228:229] op_sel_hi:[1,0]
	v_pk_mul_f32 v[18:19], v[18:19], v[228:229] op_sel_hi:[1,0]
	v_pk_mul_f32 v[16:17], v[16:17], v[228:229] op_sel_hi:[1,0]
	v_pk_mul_f32 v[14:15], v[14:15], v[228:229] op_sel_hi:[1,0]
	v_pk_mul_f32 v[12:13], v[12:13], v[228:229] op_sel_hi:[1,0]
	v_pk_mul_f32 v[10:11], v[10:11], v[228:229] op_sel_hi:[1,0]
	v_pk_mul_f32 v[8:9], v[8:9], v[228:229] op_sel_hi:[1,0]
	v_pk_mul_f32 v[6:7], v[6:7], v[228:229] op_sel_hi:[1,0]
	v_pk_mul_f32 v[4:5], v[4:5], v[228:229] op_sel_hi:[1,0]
	v_pk_mul_f32 v[2:3], v[2:3], v[228:229] op_sel_hi:[1,0]
	v_pk_mul_f32 v[0:1], v[0:1], v[228:229] op_sel_hi:[1,0]
	v_mul_f32_e32 v227, v227, v228
	v_sub_f32_e32 v93, v93, v229
	v_sub_f32_e32 v92, v92, v229
	v_sub_f32_e32 v91, v91, v229
	v_sub_f32_e32 v90, v90, v229
	v_sub_f32_e32 v89, v89, v229
	v_sub_f32_e32 v88, v88, v229
	v_sub_f32_e32 v87, v87, v229
	v_sub_f32_e32 v86, v86, v229
	v_sub_f32_e32 v85, v85, v229
	v_sub_f32_e32 v84, v84, v229
	v_sub_f32_e32 v83, v83, v229
	v_sub_f32_e32 v82, v82, v229
	v_sub_f32_e32 v81, v81, v229
	v_sub_f32_e32 v80, v80, v229
	v_sub_f32_e32 v79, v79, v229
	v_sub_f32_e32 v78, v78, v229
	v_sub_f32_e32 v77, v77, v229
	v_sub_f32_e32 v76, v76, v229
	v_sub_f32_e32 v75, v75, v229
	v_sub_f32_e32 v74, v74, v229
	v_sub_f32_e32 v73, v73, v229
	v_sub_f32_e32 v72, v72, v229
	v_sub_f32_e32 v71, v71, v229
	v_sub_f32_e32 v70, v70, v229
	v_sub_f32_e32 v69, v69, v229
	v_sub_f32_e32 v68, v68, v229
	v_sub_f32_e32 v67, v67, v229
	v_sub_f32_e32 v66, v66, v229
	v_sub_f32_e32 v65, v65, v229
	v_sub_f32_e32 v64, v64, v229
	s_branch .LBB0_134

.LBB0_158:
	v_add_f32_e32 v111, 0, v123
	v_add_f32_e32 v119, 0, v125
	v_add_f32_e32 v111, v126, v111
	v_add_f32_e32 v119, v127, v119
	v_exp_f32_e32 v127, v64
	v_exp_f32_e32 v126, v80
	v_exp_f32_e32 v65, v65
	v_exp_f32_e32 v64, v81
	v_add_f32_e32 v111, v130, v111
	v_add_f32_e32 v119, v131, v119
	v_exp_f32_e32 v131, v66
	v_exp_f32_e32 v130, v82
	v_exp_f32_e32 v67, v67
	v_exp_f32_e32 v66, v83
	v_pk_add_f32 v[80:81], v[126:127], 0 op_sel_hi:[1,0]
	v_exp_f32_e32 v83, v68
	v_exp_f32_e32 v82, v84
	v_add_f32_e32 v111, v132, v111
	v_add_f32_e32 v119, v133, v119
	v_pk_add_f32 v[80:81], v[64:65], v[80:81]
	v_exp_f32_e32 v133, v69
	v_exp_f32_e32 v132, v85
	v_add_f32_e32 v111, v134, v111
	v_pk_add_f32 v[80:81], v[130:131], v[80:81]
	v_exp_f32_e32 v85, v70
	v_exp_f32_e32 v84, v86
	v_add_f32_e32 v119, v135, v119
	v_add_f32_e32 v111, v140, v111
	v_pk_add_f32 v[80:81], v[66:67], v[80:81]
	v_exp_f32_e32 v135, v71
	v_exp_f32_e32 v134, v87
	v_add_f32_e32 v111, v142, v111
	v_exp_f32_e32 v87, v72
	v_exp_f32_e32 v86, v88
	v_pk_add_f32 v[68:69], v[82:83], v[80:81]
	v_add_f32_e32 v119, v141, v119
	v_add_f32_e32 v111, v143, v111
	v_exp_f32_e32 v141, v73
	v_exp_f32_e32 v140, v89
	v_pk_add_f32 v[68:69], v[132:133], v[68:69]
	v_add_f32_e32 v111, v146, v111
	v_exp_f32_e32 v89, v74
	v_exp_f32_e32 v88, v90
	v_pk_add_f32 v[68:69], v[84:85], v[68:69]
	v_add_f32_e32 v111, v145, v111
	v_exp_f32_e32 v143, v75
	v_exp_f32_e32 v142, v91
	v_pk_add_f32 v[68:69], v[134:135], v[68:69]
	v_add_f32_e32 v111, v144, v111
	v_exp_f32_e32 v91, v76
	v_exp_f32_e32 v90, v92
	v_pk_add_f32 v[68:69], v[86:87], v[68:69]
	v_add_f32_e32 v111, v149, v111
	v_exp_f32_e32 v145, v77
	v_exp_f32_e32 v144, v93
	v_pk_add_f32 v[68:69], v[140:141], v[68:69]
	v_add_f32_e32 v111, v148, v111
	v_exp_f32_e32 v93, v78
	v_exp_f32_e32 v92, v94
	v_pk_add_f32 v[68:69], v[88:89], v[68:69]
	v_add_f32_e32 v111, v147, v111
	v_exp_f32_e32 v147, v79
	v_exp_f32_e32 v146, v95
	v_pk_add_f32 v[68:69], v[142:143], v[68:69]
	v_cvt_pk_bf16_f32 v76, v127, v65
	v_pk_add_f32 v[68:69], v[90:91], v[68:69]
	v_cvt_pk_bf16_f32 v78, v83, v133
	v_pk_add_f32 v[68:69], v[144:145], v[68:69]
	v_cvt_pk_bf16_f32 v79, v85, v135
	v_pk_add_f32 v[68:69], v[92:93], v[68:69]
	v_cvt_pk_bf16_f32 v70, v82, v132
	v_pk_add_f32 v[68:69], v[146:147], v[68:69]
	v_cvt_pk_bf16_f32 v71, v84, v134
	v_add_f32_e32 v80, v68, v69
	v_cvt_pk_bf16_f32 v68, v126, v64
	v_cvt_pk_bf16_f32 v72, v87, v141
	v_cvt_pk_bf16_f32 v73, v89, v143
	v_cvt_pk_bf16_f32 v64, v86, v140
	v_cvt_pk_bf16_f32 v65, v88, v142
	ds_read_b128 v[82:85], v122 offset:16384
	ds_read_b128 v[86:89], v122 offset:20480
	v_cvt_pk_bf16_f32 v77, v131, v67
	v_cvt_pk_bf16_f32 v74, v91, v145
	v_cvt_pk_bf16_f32 v75, v93, v147
	s_waitcnt lgkmcnt(0)
	v_mfma_f32_32x32x16_bf16 v[0:15], v[82:85], v[76:79], v[0:15]
	ds_read_b128 v[82:85], v121 offset:20480
	v_cvt_pk_bf16_f32 v69, v130, v66
	v_add_f32_e32 v119, v154, v119
	v_add_f32_e32 v119, v153, v119
	v_add_f32_e32 v119, v152, v119
	v_add_f32_e32 v119, v156, v119
	v_add_f32_e32 v119, v155, v119
	v_mfma_f32_32x32x16_bf16 v[16:31], v[86:89], v[76:79], v[16:31]
	ds_read_b128 v[76:79], v121 offset:16384
	v_cvt_pk_bf16_f32 v66, v90, v144
	v_cvt_pk_bf16_f32 v67, v92, v146
	v_add_f32_e32 v119, v159, v119
	v_add_f32_e32 v119, v158, v119
	v_add_f32_e32 v119, v157, v119
	v_add_f32_e32 v111, v151, v111
	s_waitcnt lgkmcnt(0)
	v_mfma_f32_32x32x16_bf16 v[0:15], v[76:79], v[72:75], v[0:15]
	ds_read_b128 v[76:79], v120 offset:20480
	v_add_f32_e32 v119, v161, v119
	v_add_f32_e32 v111, v150, v111
	v_add_f32_e32 v119, v160, v119
	v_add_f32_e32 v111, v119, v111
	s_sub_i32 s11, 0x82, s13
	v_add_f32_e32 v111, 0, v111
	v_mfma_f32_32x32x16_bf16 v[16:31], v[82:85], v[72:75], v[16:31]
	ds_read_b128 v[72:75], v120 offset:16384
	s_cmp_lt_u32 s12, 64
	v_add_f32_e32 v175, v111, v80
	s_cselect_b64 s[42:43], -1, 0
	s_cmp_gt_u32 s12, 63
	s_waitcnt lgkmcnt(0)
	v_mfma_f32_32x32x16_bf16 v[0:15], v[72:75], v[68:71], v[0:15]
	ds_read_b128 v[72:75], v110 offset:20480
	v_mfma_f32_32x32x16_bf16 v[16:31], v[76:79], v[68:71], v[16:31]
	ds_read_b128 v[68:71], v110 offset:16384
	s_waitcnt vmcnt(0)
	s_waitcnt vmcnt(0) lgkmcnt(0)
	s_barrier
	v_mfma_f32_32x32x16_bf16 v[0:15], v[68:71], v[64:67], v[0:15]
	v_mfma_f32_32x32x16_bf16 v[16:31], v[72:75], v[64:67], v[16:31]
	s_cbranch_scc1 .LBB0_173
	v_add_u32_e32 v241, v115, v116
	v_add_u32_e32 v242, v115, v117
	v_add_u32_e32 v243, v118, v114
	v_add_u32_e32 v244, v118, v124
	v_add_u32_e32 v245, v118, v128
	v_add_u32_e32 v246, v118, v129
	s_mov_b64 s[100:101], s[50:51]
	v_readfirstlane_b32 s98, v109
	v_readfirstlane_b32 s99, v113
	v_lshlrev_b32_e32 v222, 1, v192
	v_lshlrev_b32_e32 v227, 1, v104
	v_lshlrev_b32_e32 v228, 1, v106
	v_lshl_add_u64 v[110:111], v[192:193], 1, s[50:51]
	s_mov_b32 s50, 2
	s_movk_i32 s12, 0x3000
	s_mov_b32 s10, 0
	s_movk_i32 s2, 0x6000
.LBB0_160:
	s_add_i32 s69, s13, s50
	s_add_i32 s70, s69, 2
	s_lshl_b64 vcc, s[70:71], 12
	s_add_u32 vcc_lo, s100, vcc_lo
	s_addc_u32 vcc_hi, s101, vcc_hi
	s_add_i32 s3, s12, 32
	s_add_i32 s8, s3, s98
	s_mov_b32 m0, s8
	s_add_i32 s3, s3, s99
	global_load_lds_dwordx4 v222, vcc
	s_lshl_b64 vcc, s[70:71], 7
	s_add_u32 vcc_lo, s19, vcc_lo
	s_addc_u32 vcc_hi, s5, vcc_hi
	s_add_i32 m0, s8, 0x1000
	s_addk_i32 s3, 0x1000
	global_load_lds_dwordx4 v227, vcc
	s_mov_b32 m0, s3
	s_mov_b32 s51, s10
	global_load_lds_dwordx4 v228, vcc
	s_add_i32 s8, s51, 32
	s_mov_b32 s10, s2
	s_mov_b64 s[2:3], -1
	s_and_b64 vcc, exec, s[28:29]
	v_add_u32_e32 v120, s8, v241
	v_add_u32_e32 v119, s8, v242
	s_cbranch_vccnz .LBB0_162
	ds_read_b128 v[64:67], v120
	ds_read_b128 v[130:133], v119
	s_mov_b64 s[2:3], 0
	s_waitcnt lgkmcnt(0)
	v_mfma_f32_32x32x16_bf16 v[80:95], v[64:67], v[100:103], 0
	ds_read_b128 v[64:67], v120 offset:2048
	v_mfma_f32_32x32x16_bf16 v[80:95], v[130:133], v[96:99], v[80:95]
	ds_read_b128 v[130:133], v119 offset:2048
	s_waitcnt lgkmcnt(0)
	v_mfma_f32_32x32x16_bf16 v[64:79], v[64:67], v[100:103], 0
	v_mfma_f32_32x32x16_bf16 v[64:79], v[130:133], v[96:99], v[64:79]

.LBB0_167:
	v_exp_f32_e32 v142, v56
	v_exp_f32_e32 v130, v52
	v_add_u32_e32 v52, s10, v243
	v_exp_f32_e32 v119, v48
	v_exp_f32_e32 v121, v49
	v_exp_f32_e32 v123, v50
	v_exp_f32_e32 v126, v51
	v_exp_f32_e32 v132, v53
	v_exp_f32_e32 v134, v54
	v_exp_f32_e32 v140, v55
	ds_read_b128 v[48:51], v52 offset:4096
	ds_read_b128 v[52:55], v52 offset:8192
	v_exp_f32_e32 v151, v44
	v_exp_f32_e32 v153, v45
	v_exp_f32_e32 v155, v46
	v_exp_f32_e32 v157, v47
	v_cvt_pk_bf16_f32 v44, v119, v121
	v_cvt_pk_bf16_f32 v45, v123, v126
	v_cvt_pk_bf16_f32 v46, v130, v132
	v_cvt_pk_bf16_f32 v47, v134, v140
	v_exp_f32_e32 v144, v57
	v_exp_f32_e32 v146, v58
	s_waitcnt lgkmcnt(0)
	v_mfma_f32_32x32x16_bf16 v[0:15], v[48:51], v[44:47], v[0:15]
	v_add_u32_e32 v48, s10, v244
	v_exp_f32_e32 v148, v59
	v_exp_f32_e32 v150, v60
	v_exp_f32_e32 v152, v61
	v_exp_f32_e32 v154, v62
	v_exp_f32_e32 v156, v63
	v_exp_f32_e32 v143, v40
	v_mfma_f32_32x32x16_bf16 v[16:31], v[52:55], v[44:47], v[16:31]
	ds_read_b128 v[44:47], v48 offset:4096
	ds_read_b128 v[48:51], v48 offset:8192
	v_exp_f32_e32 v145, v41
	v_exp_f32_e32 v147, v42
	v_exp_f32_e32 v149, v43
	v_cvt_pk_bf16_f32 v40, v142, v144
	v_cvt_pk_bf16_f32 v41, v146, v148
	v_cvt_pk_bf16_f32 v42, v150, v152
	v_cvt_pk_bf16_f32 v43, v154, v156
	v_exp_f32_e32 v120, v32
	v_exp_f32_e32 v122, v33
	s_waitcnt lgkmcnt(0)
	v_mfma_f32_32x32x16_bf16 v[0:15], v[44:47], v[40:43], v[0:15]
	v_add_u32_e32 v44, s10, v245
	v_exp_f32_e32 v125, v34
	v_exp_f32_e32 v127, v35
	v_exp_f32_e32 v131, v36
	v_exp_f32_e32 v133, v37
	v_exp_f32_e32 v135, v38
	v_exp_f32_e32 v141, v39
	v_mfma_f32_32x32x16_bf16 v[16:31], v[48:51], v[40:43], v[16:31]
	ds_read_b128 v[40:43], v44 offset:4096
	ds_read_b128 v[44:47], v44 offset:8192
	v_cvt_pk_bf16_f32 v36, v120, v122
	v_cvt_pk_bf16_f32 v37, v125, v127
	v_cvt_pk_bf16_f32 v38, v131, v133
	v_cvt_pk_bf16_f32 v39, v135, v141
	s_add_i32 s70, s69, 3
	s_lshl_b64 s[2:3], s[70:71], 12
	s_waitcnt lgkmcnt(0)
	v_mfma_f32_32x32x16_bf16 v[0:15], v[40:43], v[36:39], v[0:15]
	v_add_u32_e32 v40, s10, v246
	v_cvt_pk_bf16_f32 v32, v143, v145
	v_cvt_pk_bf16_f32 v33, v147, v149
	v_cvt_pk_bf16_f32 v34, v151, v153
	v_cvt_pk_bf16_f32 v35, v155, v157
	s_cmp_lg_u32 32, -1
	v_mfma_f32_32x32x16_bf16 v[16:31], v[44:47], v[36:39], v[16:31]
	ds_read_b128 v[36:39], v40 offset:4096
	ds_read_b128 v[40:43], v40 offset:8192
	s_waitcnt vmcnt(0)
	s_waitcnt vmcnt(0) lgkmcnt(0)
	s_barrier
	v_mfma_f32_32x32x16_bf16 v[0:15], v[36:39], v[32:35], v[0:15]
	v_mfma_f32_32x32x16_bf16 v[16:31], v[40:43], v[32:35], v[16:31]
	s_add_u32 s2, s100, s2
	s_addc_u32 s3, s101, s3
	s_add_i32 s69, s10, 32
	s_add_i32 vcc_lo, s69, s98
	s_mov_b32 m0, vcc_lo
	s_add_i32 vcc_hi, s69, s99
	global_load_lds_dwordx4 v222, s[2:3]
	s_lshl_b64 s[2:3], s[70:71], 7
	s_add_u32 s2, s19, s2
	s_addc_u32 s3, s5, s3
	s_add_i32 m0, vcc_lo, 0x1000
	s_add_i32 s69, s12, 32
	global_load_lds_dwordx4 v227, s[2:3]
	s_add_i32 m0, vcc_hi, 0x1000
	s_nop 0
	global_load_lds_dwordx4 v228, s[2:3]
	s_mov_b64 s[2:3], -1
	s_and_b64 vcc, exec, s[28:29]
	v_add_u32_e32 v159, s69, v241
	v_add_u32_e32 v158, s69, v242
	s_cbranch_vccnz .LBB0_169
	ds_read_b128 v[32:35], v159
	ds_read_b128 v[160:163], v158
	s_mov_b64 s[2:3], 0
	s_waitcnt lgkmcnt(0)
	v_mfma_f32_32x32x16_bf16 v[48:63], v[32:35], v[100:103], 0
	ds_read_b128 v[32:35], v159 offset:2048
	v_mfma_f32_32x32x16_bf16 v[48:63], v[160:163], v[96:99], v[48:63]
	ds_read_b128 v[160:163], v158 offset:2048
	s_waitcnt lgkmcnt(0)
	v_mfma_f32_32x32x16_bf16 v[32:47], v[32:35], v[100:103], 0
	v_mfma_f32_32x32x16_bf16 v[32:47], v[160:163], v[96:99], v[32:47]

.LBB0_171:
	v_add_f32_e32 v119, v121, v119
	v_add_f32_e32 v120, v122, v120
	v_add_f32_e32 v119, v123, v119
	v_add_f32_e32 v120, v125, v120
	v_add_f32_e32 v119, v126, v119
	v_add_f32_e32 v120, v127, v120
	v_add_f32_e32 v119, v130, v119
	v_exp_f32_e32 v125, v80
	v_exp_f32_e32 v130, v64
	v_add_f32_e32 v120, v131, v120
	v_add_f32_e32 v119, v132, v119
	v_exp_f32_e32 v131, v81
	v_exp_f32_e32 v132, v65
	v_add_f32_e32 v120, v133, v120
	v_add_f32_e32 v119, v134, v119
	v_exp_f32_e32 v133, v82
	v_exp_f32_e32 v134, v66
	v_add_f32_e32 v120, v135, v120
	v_add_f32_e32 v119, v140, v119
	v_exp_f32_e32 v135, v83
	v_exp_f32_e32 v140, v67
	v_add_f32_e32 v120, v141, v120
	v_add_f32_e32 v119, v142, v119
	v_add_f32_e32 v120, v143, v120
	v_add_f32_e32 v64, v131, v125
	v_add_f32_e32 v65, v132, v130
	v_add_f32_e32 v119, v144, v119
	v_add_f32_e32 v120, v145, v120
	v_add_f32_e32 v64, v133, v64
	v_add_f32_e32 v66, v134, v65
	v_add_f32_e32 v119, v146, v119
	v_add_f32_e32 v120, v147, v120
	v_add_f32_e32 v65, v135, v64
	v_add_f32_e32 v64, v140, v66
	v_exp_f32_e32 v67, v84
	v_exp_f32_e32 v66, v68
	v_add_f32_e32 v119, v148, v119
	v_add_f32_e32 v120, v149, v120
	v_exp_f32_e32 v81, v85
	v_exp_f32_e32 v80, v69
	v_add_f32_e32 v119, v150, v119
	v_add_f32_e32 v120, v151, v120
	v_exp_f32_e32 v83, v86
	v_exp_f32_e32 v82, v70
	v_add_f32_e32 v119, v152, v119
	v_add_f32_e32 v120, v153, v120
	v_exp_f32_e32 v85, v87
	v_exp_f32_e32 v84, v71
	v_add_f32_e32 v119, v154, v119
	v_add_f32_e32 v120, v155, v120
	v_exp_f32_e32 v87, v88
	v_exp_f32_e32 v86, v72
	v_add_f32_e32 v64, v66, v64
	v_add_f32_e32 v65, v67, v65
	v_add_f32_e32 v119, v156, v119
	v_add_f32_e32 v120, v157, v120
	v_exp_f32_e32 v89, v89
	v_exp_f32_e32 v88, v73
	v_add_f32_e32 v64, v80, v64
	v_add_f32_e32 v65, v81, v65
	v_add_f32_e32 v119, v120, v119
	v_exp_f32_e32 v121, v90
	v_exp_f32_e32 v120, v74
	v_add_f32_e32 v64, v82, v64
	v_add_f32_e32 v65, v83, v65
	v_exp_f32_e32 v91, v91
	v_exp_f32_e32 v90, v75
	v_add_f32_e32 v64, v84, v64
	v_add_f32_e32 v65, v85, v65
	v_exp_f32_e32 v123, v92
	v_exp_f32_e32 v122, v76
	v_add_f32_e32 v64, v86, v64
	v_add_f32_e32 v65, v87, v65
	v_exp_f32_e32 v93, v93
	v_exp_f32_e32 v92, v77
	v_add_f32_e32 v64, v88, v64
	v_add_f32_e32 v65, v89, v65
	v_exp_f32_e32 v127, v94
	v_exp_f32_e32 v126, v78
	v_add_f32_e32 v64, v120, v64
	v_add_f32_e32 v65, v121, v65
	v_exp_f32_e32 v95, v95
	v_exp_f32_e32 v94, v79
	v_add_f32_e32 v64, v90, v64
	v_add_f32_e32 v65, v91, v65
	v_cvt_pk_bf16_f32 v71, v82, v84
	v_add_f32_e32 v64, v122, v64
	v_add_f32_e32 v65, v123, v65
	v_cvt_pk_bf16_f32 v78, v67, v81
	v_add_f32_e32 v64, v92, v64
	v_add_f32_e32 v65, v93, v65
	v_cvt_pk_bf16_f32 v79, v83, v85
	v_add_f32_e32 v64, v126, v64
	v_add_f32_e32 v65, v127, v65
	v_cvt_pk_bf16_f32 v70, v66, v80
	v_add_f32_e32 v64, v94, v64
	v_add_f32_e32 v65, v95, v65
	v_cvt_pk_bf16_f32 v72, v87, v89
	v_add_f32_e32 v141, v64, v65
	v_cvt_pk_bf16_f32 v64, v86, v88
	v_add_u32_e32 v84, s51, v243
	ds_read_b128 v[80:83], v84 offset:4096
	ds_read_b128 v[84:87], v84 offset:8192
	v_cvt_pk_bf16_f32 v76, v125, v131
	v_cvt_pk_bf16_f32 v77, v133, v135
	v_cvt_pk_bf16_f32 v73, v121, v91
	v_cvt_pk_bf16_f32 v74, v123, v93
	s_waitcnt lgkmcnt(0)
	v_mfma_f32_32x32x16_bf16 v[0:15], v[80:83], v[76:79], v[0:15]
	v_add_u32_e32 v80, s51, v244
	v_cvt_pk_bf16_f32 v75, v127, v95
	v_cvt_pk_bf16_f32 v68, v130, v132
	v_cvt_pk_bf16_f32 v69, v134, v140
	v_cvt_pk_bf16_f32 v65, v120, v90
	v_cvt_pk_bf16_f32 v66, v122, v92
	v_cvt_pk_bf16_f32 v67, v126, v94
	v_mfma_f32_32x32x16_bf16 v[16:31], v[84:87], v[76:79], v[16:31]
	ds_read_b128 v[76:79], v80 offset:4096
	ds_read_b128 v[80:83], v80 offset:8192
	v_add_f32_e32 v119, v175, v119
	s_add_i32 s50, s50, 2
	v_add_f32_e32 v175, v141, v119
	s_cmp_lt_u32 s50, s11
	s_waitcnt lgkmcnt(0)
	v_mfma_f32_32x32x16_bf16 v[0:15], v[76:79], v[72:75], v[0:15]
	v_add_u32_e32 v76, s51, v245
	v_mfma_f32_32x32x16_bf16 v[16:31], v[80:83], v[72:75], v[16:31]
	ds_read_b128 v[72:75], v76 offset:4096
	ds_read_b128 v[76:79], v76 offset:8192
	s_waitcnt lgkmcnt(0)
	v_mfma_f32_32x32x16_bf16 v[0:15], v[72:75], v[68:71], v[0:15]
	v_add_u32_e32 v72, s51, v246
	v_mfma_f32_32x32x16_bf16 v[16:31], v[76:79], v[68:71], v[16:31]
	ds_read_b128 v[68:71], v72 offset:4096
	ds_read_b128 v[72:75], v72 offset:8192
	s_waitcnt vmcnt(0)
	s_waitcnt vmcnt(0) lgkmcnt(0)
	s_barrier
	v_mfma_f32_32x32x16_bf16 v[0:15], v[68:71], v[64:67], v[0:15]
	v_mfma_f32_32x32x16_bf16 v[16:31], v[72:75], v[64:67], v[16:31]
	s_cbranch_scc0 .LBB0_174
	s_mov_b32 s2, s12
	s_mov_b32 s12, s51
	s_branch .LBB0_160

.LBB0_189:
	v_add_f32_e32 v152, 0, v152
	v_add_f32_e32 v153, 0, v153
	v_add_f32_e32 v152, v154, v152
	v_add_f32_e32 v153, v155, v153
	v_exp_f32_e32 v155, v96
	v_exp_f32_e32 v154, v112
	v_exp_f32_e32 v97, v97
	v_exp_f32_e32 v96, v113
	v_add_f32_e32 v152, v156, v152
	v_add_f32_e32 v153, v157, v153
	v_exp_f32_e32 v157, v98
	v_exp_f32_e32 v156, v114
	v_exp_f32_e32 v99, v99
	v_exp_f32_e32 v98, v115
	v_pk_add_f32 v[112:113], v[154:155], 0 op_sel_hi:[1,0]
	v_exp_f32_e32 v115, v100
	v_exp_f32_e32 v114, v116
	v_add_f32_e32 v152, v158, v152
	v_add_f32_e32 v153, v159, v153
	v_pk_add_f32 v[112:113], v[96:97], v[112:113]
	v_exp_f32_e32 v159, v101
	v_exp_f32_e32 v158, v117
	v_pk_add_f32 v[112:113], v[156:157], v[112:113]
	v_exp_f32_e32 v117, v102
	v_exp_f32_e32 v116, v118
	v_add_f32_e32 v152, v160, v152
	v_add_f32_e32 v153, v161, v153
	v_pk_add_f32 v[112:113], v[98:99], v[112:113]
	v_exp_f32_e32 v161, v103
	v_exp_f32_e32 v160, v119
	v_exp_f32_e32 v119, v104
	v_exp_f32_e32 v118, v120
	v_pk_add_f32 v[100:101], v[114:115], v[112:113]
	v_add_f32_e32 v152, v162, v152
	v_add_f32_e32 v153, v163, v153
	v_exp_f32_e32 v163, v105
	v_exp_f32_e32 v162, v121
	v_pk_add_f32 v[100:101], v[158:159], v[100:101]
	v_exp_f32_e32 v121, v106
	v_exp_f32_e32 v120, v122
	v_pk_add_f32 v[100:101], v[116:117], v[100:101]
	v_add_f32_e32 v152, v164, v152
	v_add_f32_e32 v153, v165, v153
	v_exp_f32_e32 v165, v107
	v_exp_f32_e32 v164, v123
	v_pk_add_f32 v[100:101], v[160:161], v[100:101]
	v_exp_f32_e32 v123, v108
	v_exp_f32_e32 v122, v124
	v_pk_add_f32 v[100:101], v[118:119], v[100:101]
	v_add_f32_e32 v152, v166, v152
	v_add_f32_e32 v153, v167, v153
	v_exp_f32_e32 v167, v109
	v_exp_f32_e32 v166, v125
	v_pk_add_f32 v[100:101], v[162:163], v[100:101]
	v_exp_f32_e32 v125, v110
	v_exp_f32_e32 v124, v126
	v_pk_add_f32 v[100:101], v[120:121], v[100:101]
	v_add_f32_e32 v152, v168, v152
	v_add_f32_e32 v153, v169, v153
	v_exp_f32_e32 v169, v111
	v_exp_f32_e32 v168, v127
	v_pk_add_f32 v[100:101], v[164:165], v[100:101]
	v_cvt_pk_bf16_f32 v108, v155, v97
	v_pk_add_f32 v[100:101], v[122:123], v[100:101]
	v_cvt_pk_bf16_f32 v110, v115, v159
	v_pk_add_f32 v[100:101], v[166:167], v[100:101]
	v_cvt_pk_bf16_f32 v111, v117, v161
	v_pk_add_f32 v[100:101], v[124:125], v[100:101]
	v_cvt_pk_bf16_f32 v102, v114, v158
	v_pk_add_f32 v[100:101], v[168:169], v[100:101]
	v_cvt_pk_bf16_f32 v103, v116, v160
	v_add_f32_e32 v112, v100, v101
	v_cvt_pk_bf16_f32 v100, v154, v96
	v_cvt_pk_bf16_f32 v104, v119, v163
	v_cvt_pk_bf16_f32 v105, v121, v165
	v_cvt_pk_bf16_f32 v96, v118, v162
	v_cvt_pk_bf16_f32 v97, v120, v164
	ds_read_b128 v[114:117], v151 offset:16384
	ds_read_b128 v[118:121], v151 offset:20480
	v_cvt_pk_bf16_f32 v109, v157, v99
	v_cvt_pk_bf16_f32 v106, v123, v167
	v_cvt_pk_bf16_f32 v107, v125, v169
	s_waitcnt lgkmcnt(0)
	v_mfma_f32_32x32x16_bf16 v[32:47], v[114:117], v[108:111], v[32:47]
	ds_read_b128 v[114:117], v150 offset:20480
	v_cvt_pk_bf16_f32 v101, v156, v98
	v_add_f32_e32 v152, v175, v152
	v_add_f32_e32 v153, v184, v153
	v_add_f32_e32 v152, v185, v152
	v_add_f32_e32 v153, v186, v153
	v_cvt_pk_bf16_f32 v98, v122, v166
	v_mfma_f32_32x32x16_bf16 v[48:63], v[118:121], v[108:111], v[48:63]
	ds_read_b128 v[108:111], v150 offset:16384
	v_cvt_pk_bf16_f32 v99, v124, v168
	v_add_f32_e32 v152, v187, v152
	v_add_f32_e32 v153, v188, v153
	v_add_f32_e32 v152, v189, v152
	v_add_f32_e32 v153, v190, v153
	v_add_f32_e32 v152, v191, v152
	s_waitcnt lgkmcnt(0)
	v_mfma_f32_32x32x16_bf16 v[32:47], v[108:111], v[104:107], v[32:47]
	ds_read_b128 v[108:111], v147 offset:20480
	v_add_f32_e32 v153, v206, v153
	v_add_f32_e32 v152, v210, v152
	v_add_f32_e32 v153, v212, v153
	v_add_f32_e32 v152, v213, v152
	v_add_f32_e32 v153, v214, v153
	v_add_f32_e32 v152, v153, v152
	v_mfma_f32_32x32x16_bf16 v[48:63], v[114:117], v[104:107], v[48:63]
	ds_read_b128 v[104:107], v147 offset:16384
	v_add_f32_e32 v152, 0, v152
	v_add_f32_e32 v184, v152, v112
	s_andn2_b64 vcc, exec, s[42:43]
	s_waitcnt lgkmcnt(0)
	v_mfma_f32_32x32x16_bf16 v[32:47], v[104:107], v[100:103], v[32:47]
	ds_read_b128 v[104:107], v146 offset:20480
	v_mfma_f32_32x32x16_bf16 v[48:63], v[108:111], v[100:103], v[48:63]
	ds_read_b128 v[100:103], v146 offset:16384
	s_waitcnt vmcnt(0)
	s_waitcnt vmcnt(0) lgkmcnt(0)
	s_barrier
	v_mfma_f32_32x32x16_bf16 v[32:47], v[100:103], v[96:99], v[32:47]
	v_mfma_f32_32x32x16_bf16 v[48:63], v[104:107], v[96:99], v[48:63]
	s_cbranch_vccnz .LBB0_204
	v_add_u32_e32 v241, v172, v173
	v_add_u32_e32 v242, v172, v174
	v_add_u32_e32 v243, v149, v180
	v_add_u32_e32 v244, v149, v181
	v_add_u32_e32 v245, v149, v182
	v_add_u32_e32 v246, v149, v183
	s_mov_b64 s[100:101], s[50:51]
	v_readfirstlane_b32 s98, v170
	v_readfirstlane_b32 s99, v171
	v_lshlrev_b32_e32 v222, 1, v192
	v_lshlrev_b32_e32 v227, 1, v140
	v_lshlrev_b32_e32 v228, 1, v142
	v_lshl_add_u64 v[146:147], v[192:193], 1, s[50:51]
	s_mov_b32 s17, 2
	s_movk_i32 s12, 0x3000
	s_mov_b32 s16, 0
	s_movk_i32 s2, 0x6000
.LBB0_191:
	s_add_i32 s8, s13, s17
	s_add_i32 s70, s8, 2
	s_lshl_b64 s[42:43], s[70:71], 12
	s_add_u32 s42, s100, s42
	s_addc_u32 s43, s101, s43
	s_add_i32 s3, s12, 32
	s_add_i32 s10, s3, s98
	s_mov_b32 m0, s10
	s_add_i32 s3, s3, s99
	global_load_lds_dwordx4 v222, s[42:43]
	s_lshl_b64 s[42:43], s[70:71], 7
	s_add_u32 s42, s19, s42
	s_addc_u32 s43, s5, s43
	s_add_i32 m0, s10, 0x1000
	s_addk_i32 s3, 0x1000
	global_load_lds_dwordx4 v227, s[42:43]
	s_mov_b32 m0, s3
	s_mov_b32 s10, s16
	global_load_lds_dwordx4 v228, s[42:43]
	s_add_i32 s42, s10, 32
	s_mov_b32 s16, s2
	s_mov_b64 s[2:3], -1
	s_and_b64 vcc, exec, s[28:29]
	v_add_u32_e32 v151, s42, v241
	v_add_u32_e32 v150, s42, v242
	s_cbranch_vccnz .LBB0_193
	ds_read_b128 v[96:99], v151
	ds_read_b128 v[152:155], v150
	s_mov_b64 s[2:3], 0
	s_waitcnt lgkmcnt(0)
	v_mfma_f32_32x32x16_bf16 v[112:127], v[96:99], v[132:135], 0
	ds_read_b128 v[96:99], v151 offset:2048
	v_mfma_f32_32x32x16_bf16 v[112:127], v[152:155], v[128:131], v[112:127]
	ds_read_b128 v[152:155], v150 offset:2048
	s_waitcnt lgkmcnt(0)
	v_mfma_f32_32x32x16_bf16 v[96:111], v[96:99], v[132:135], 0
	v_mfma_f32_32x32x16_bf16 v[96:111], v[152:155], v[128:131], v[96:111]

.LBB0_198:
	v_exp_f32_e32 v166, v88
	v_exp_f32_e32 v158, v84
	v_add_u32_e32 v84, s16, v243
	v_exp_f32_e32 v150, v80
	v_exp_f32_e32 v152, v81
	v_exp_f32_e32 v154, v82
	v_exp_f32_e32 v156, v83
	v_exp_f32_e32 v160, v85
	v_exp_f32_e32 v162, v86
	v_exp_f32_e32 v164, v87
	ds_read_b128 v[80:83], v84 offset:4096
	ds_read_b128 v[84:87], v84 offset:8192
	v_exp_f32_e32 v187, v76
	v_exp_f32_e32 v189, v77
	v_exp_f32_e32 v191, v78
	v_exp_f32_e32 v206, v79
	v_cvt_pk_bf16_f32 v76, v150, v152
	v_cvt_pk_bf16_f32 v77, v154, v156
	v_cvt_pk_bf16_f32 v78, v158, v160
	v_cvt_pk_bf16_f32 v79, v162, v164
	v_exp_f32_e32 v168, v89
	v_exp_f32_e32 v175, v90
	s_waitcnt lgkmcnt(0)
	v_mfma_f32_32x32x16_bf16 v[32:47], v[80:83], v[76:79], v[32:47]
	v_add_u32_e32 v80, s16, v244
	v_exp_f32_e32 v177, v91
	v_exp_f32_e32 v186, v92
	v_exp_f32_e32 v188, v93
	v_exp_f32_e32 v190, v94
	v_exp_f32_e32 v192, v95
	v_exp_f32_e32 v167, v72
	v_mfma_f32_32x32x16_bf16 v[48:63], v[84:87], v[76:79], v[48:63]
	ds_read_b128 v[76:79], v80 offset:4096
	ds_read_b128 v[80:83], v80 offset:8192
	v_exp_f32_e32 v169, v73
	v_exp_f32_e32 v176, v74
	v_exp_f32_e32 v185, v75
	v_cvt_pk_bf16_f32 v72, v166, v168
	v_cvt_pk_bf16_f32 v73, v175, v177
	v_cvt_pk_bf16_f32 v74, v186, v188
	v_cvt_pk_bf16_f32 v75, v190, v192
	v_exp_f32_e32 v151, v64
	v_exp_f32_e32 v153, v65
	s_waitcnt lgkmcnt(0)
	v_mfma_f32_32x32x16_bf16 v[32:47], v[76:79], v[72:75], v[32:47]
	v_add_u32_e32 v76, s16, v245
	v_exp_f32_e32 v155, v66
	v_exp_f32_e32 v157, v67
	v_exp_f32_e32 v159, v68
	v_exp_f32_e32 v161, v69
	v_exp_f32_e32 v163, v70
	v_exp_f32_e32 v165, v71
	v_mfma_f32_32x32x16_bf16 v[48:63], v[80:83], v[72:75], v[48:63]
	ds_read_b128 v[72:75], v76 offset:4096
	ds_read_b128 v[76:79], v76 offset:8192
	v_cvt_pk_bf16_f32 v68, v151, v153
	v_cvt_pk_bf16_f32 v69, v155, v157
	v_cvt_pk_bf16_f32 v70, v159, v161
	v_cvt_pk_bf16_f32 v71, v163, v165
	s_add_i32 s70, s8, 3
	s_lshl_b64 s[2:3], s[70:71], 12
	s_waitcnt lgkmcnt(0)
	v_mfma_f32_32x32x16_bf16 v[32:47], v[72:75], v[68:71], v[32:47]
	v_add_u32_e32 v72, s16, v246
	v_cvt_pk_bf16_f32 v64, v167, v169
	v_cvt_pk_bf16_f32 v65, v176, v185
	v_cvt_pk_bf16_f32 v66, v187, v189
	v_cvt_pk_bf16_f32 v67, v191, v206
	s_cmp_lg_u32 32, -1
	v_mfma_f32_32x32x16_bf16 v[48:63], v[76:79], v[68:71], v[48:63]
	ds_read_b128 v[68:71], v72 offset:4096
	ds_read_b128 v[72:75], v72 offset:8192
	s_waitcnt vmcnt(0)
	s_waitcnt vmcnt(0) lgkmcnt(0)
	s_barrier
	v_mfma_f32_32x32x16_bf16 v[32:47], v[68:71], v[64:67], v[32:47]
	v_mfma_f32_32x32x16_bf16 v[48:63], v[72:75], v[64:67], v[48:63]
	s_add_u32 s2, s100, s2
	s_addc_u32 s3, s101, s3
	s_add_i32 s8, s16, 32
	s_add_i32 s43, s8, s98
	s_mov_b32 m0, s43
	s_add_i32 s8, s8, s99
	global_load_lds_dwordx4 v222, s[2:3]
	s_lshl_b64 s[2:3], s[70:71], 7
	s_add_u32 s2, s19, s2
	s_addc_u32 s3, s5, s3
	s_add_i32 m0, s43, 0x1000
	s_addk_i32 s8, 0x1000
	global_load_lds_dwordx4 v227, s[2:3]
	s_mov_b32 m0, s8
	s_add_i32 s8, s12, 32
	global_load_lds_dwordx4 v228, s[2:3]
	s_mov_b64 s[2:3], -1
	s_and_b64 vcc, exec, s[28:29]
	v_add_u32_e32 v212, s8, v241
	v_add_u32_e32 v210, s8, v242
	s_cbranch_vccnz .LBB0_200
	ds_read_b128 v[64:67], v212
	ds_read_b128 v[214:217], v210
	s_mov_b64 s[2:3], 0
	s_waitcnt lgkmcnt(0)
	v_mfma_f32_32x32x16_bf16 v[80:95], v[64:67], v[132:135], 0
	ds_read_b128 v[64:67], v212 offset:2048
	v_mfma_f32_32x32x16_bf16 v[80:95], v[214:217], v[128:131], v[80:95]
	ds_read_b128 v[214:217], v210 offset:2048
	s_waitcnt lgkmcnt(0)
	v_mfma_f32_32x32x16_bf16 v[64:79], v[64:67], v[132:135], 0
	v_mfma_f32_32x32x16_bf16 v[64:79], v[214:217], v[128:131], v[64:79]

.LBB0_202:
	v_add_f32_e32 v150, v152, v150
	v_add_f32_e32 v151, v153, v151
	v_add_f32_e32 v150, v154, v150
	v_add_f32_e32 v151, v155, v151
	v_add_f32_e32 v150, v156, v150
	v_add_f32_e32 v151, v157, v151
	v_add_f32_e32 v150, v158, v150
	v_add_f32_e32 v151, v159, v151
	v_add_f32_e32 v150, v160, v150
	v_add_f32_e32 v151, v161, v151
	v_add_f32_e32 v150, v162, v150
	v_add_f32_e32 v151, v163, v151
	v_add_f32_e32 v150, v164, v150
	v_add_f32_e32 v151, v165, v151
	v_add_f32_e32 v150, v166, v150
	v_add_f32_e32 v151, v167, v151
	v_add_f32_e32 v150, v168, v150
	v_add_f32_e32 v151, v169, v151
	v_add_f32_e32 v150, v175, v150
	v_add_f32_e32 v151, v176, v151
	v_add_f32_e32 v150, v177, v150
	v_add_f32_e32 v151, v185, v151
	v_add_f32_e32 v150, v186, v150
	v_add_f32_e32 v151, v187, v151
	v_add_f32_e32 v150, v188, v150
	v_add_f32_e32 v151, v189, v151
	v_add_f32_e32 v150, v190, v150
	v_add_f32_e32 v151, v191, v151
	v_add_f32_e32 v150, v192, v150
	v_add_f32_e32 v151, v206, v151
	v_add_f32_e32 v150, v151, v150
	v_exp_f32_e32 v151, v112
	v_exp_f32_e32 v160, v96
	v_exp_f32_e32 v113, v113
	v_exp_f32_e32 v161, v97
	v_exp_f32_e32 v162, v114
	v_exp_f32_e32 v163, v98
	v_exp_f32_e32 v164, v115
	v_exp_f32_e32 v165, v99
	v_add_f32_e32 v96, v113, v151
	v_add_f32_e32 v97, v161, v160
	v_add_f32_e32 v96, v162, v96
	v_add_f32_e32 v98, v163, v97
	v_add_f32_e32 v97, v164, v96
	v_add_f32_e32 v96, v165, v98
	v_exp_f32_e32 v99, v116
	v_exp_f32_e32 v98, v100
	v_exp_f32_e32 v115, v117
	v_exp_f32_e32 v114, v101
	v_exp_f32_e32 v117, v118
	v_exp_f32_e32 v116, v102
	v_exp_f32_e32 v119, v119
	v_exp_f32_e32 v118, v103
	v_exp_f32_e32 v153, v120
	v_exp_f32_e32 v152, v104
	v_add_f32_e32 v96, v98, v96
	v_add_f32_e32 v97, v99, v97
	v_exp_f32_e32 v121, v121
	v_exp_f32_e32 v120, v105
	v_add_f32_e32 v96, v114, v96
	v_add_f32_e32 v97, v115, v97
	v_exp_f32_e32 v155, v122
	v_exp_f32_e32 v154, v106
	v_add_f32_e32 v96, v116, v96
	v_add_f32_e32 v97, v117, v97
	v_exp_f32_e32 v123, v123
	v_exp_f32_e32 v122, v107
	v_add_f32_e32 v96, v118, v96
	v_add_f32_e32 v97, v119, v97
	v_exp_f32_e32 v157, v124
	v_exp_f32_e32 v156, v108
	v_add_f32_e32 v96, v152, v96
	v_add_f32_e32 v97, v153, v97
	v_exp_f32_e32 v125, v125
	v_exp_f32_e32 v124, v109
	v_add_f32_e32 v96, v120, v96
	v_add_f32_e32 v97, v121, v97
	v_exp_f32_e32 v159, v126
	v_exp_f32_e32 v158, v110
	v_add_f32_e32 v96, v154, v96
	v_add_f32_e32 v97, v155, v97
	v_exp_f32_e32 v127, v127
	v_exp_f32_e32 v126, v111
	v_add_f32_e32 v96, v122, v96
	v_add_f32_e32 v97, v123, v97
	v_cvt_pk_bf16_f32 v108, v151, v113
	v_add_f32_e32 v96, v156, v96
	v_add_f32_e32 v97, v157, v97
	v_add_f32_e32 v96, v124, v96
	v_add_f32_e32 v97, v125, v97
	v_cvt_pk_bf16_f32 v103, v116, v118
	v_add_f32_e32 v96, v158, v96
	v_add_f32_e32 v97, v159, v97
	v_add_u32_e32 v118, s10, v243
	v_add_f32_e32 v96, v126, v96
	v_add_f32_e32 v97, v127, v97
	v_cvt_pk_bf16_f32 v110, v99, v115
	v_cvt_pk_bf16_f32 v111, v117, v119
	v_cvt_pk_bf16_f32 v102, v98, v114
	ds_read_b128 v[114:117], v118 offset:4096
	v_add_f32_e32 v112, v96, v97
	v_cvt_pk_bf16_f32 v104, v153, v121
	v_cvt_pk_bf16_f32 v96, v152, v120
	ds_read_b128 v[118:121], v118 offset:8192
	v_cvt_pk_bf16_f32 v109, v162, v164
	v_cvt_pk_bf16_f32 v105, v155, v123
	v_cvt_pk_bf16_f32 v106, v157, v125
	s_waitcnt lgkmcnt(0)
	v_mfma_f32_32x32x16_bf16 v[32:47], v[114:117], v[108:111], v[32:47]
	v_add_u32_e32 v114, s10, v244
	v_cvt_pk_bf16_f32 v107, v159, v127
	v_cvt_pk_bf16_f32 v100, v160, v161
	v_cvt_pk_bf16_f32 v101, v163, v165
	v_cvt_pk_bf16_f32 v97, v154, v122
	v_cvt_pk_bf16_f32 v98, v156, v124
	v_cvt_pk_bf16_f32 v99, v158, v126
	v_mfma_f32_32x32x16_bf16 v[48:63], v[118:121], v[108:111], v[48:63]
	ds_read_b128 v[108:111], v114 offset:4096
	ds_read_b128 v[114:117], v114 offset:8192
	v_add_f32_e32 v150, v184, v150
	s_add_i32 s17, s17, 2
	v_add_f32_e32 v184, v112, v150
	s_cmp_lt_u32 s17, s11
	s_waitcnt lgkmcnt(0)
	v_mfma_f32_32x32x16_bf16 v[32:47], v[108:111], v[104:107], v[32:47]
	v_add_u32_e32 v108, s10, v245
	v_mfma_f32_32x32x16_bf16 v[48:63], v[114:117], v[104:107], v[48:63]
	ds_read_b128 v[104:107], v108 offset:4096
	ds_read_b128 v[108:111], v108 offset:8192
	s_waitcnt lgkmcnt(0)
	v_mfma_f32_32x32x16_bf16 v[32:47], v[104:107], v[100:103], v[32:47]
	v_add_u32_e32 v104, s10, v246
	v_mfma_f32_32x32x16_bf16 v[48:63], v[108:111], v[100:103], v[48:63]
	ds_read_b128 v[100:103], v104 offset:4096
	ds_read_b128 v[104:107], v104 offset:8192
	s_waitcnt vmcnt(0)
	s_waitcnt vmcnt(0) lgkmcnt(0)
	s_barrier
	v_mfma_f32_32x32x16_bf16 v[32:47], v[100:103], v[96:99], v[32:47]
	v_mfma_f32_32x32x16_bf16 v[48:63], v[104:107], v[96:99], v[48:63]
	s_cbranch_scc0 .LBB0_205
	s_mov_b32 s2, s12
	s_mov_b32 s12, s10
	s_branch .LBB0_191
